# gatenorm group-RMS reductions via DPP scan + readlane instead of 12 ds_bpermute round trips per site (on top of finalize load hoisting etc.)
# speedup vs baseline: 1.0319x; 1.0045x over previous
; DI float bflo(unsigned w) { return __uint_as_float(w << 16); }
; DI float bfhi(unsigned w) { return __uint_as_float(w & 0xffff0000u); }
; DI float silu_f(float g) { return g * __builtin_amdgcn_rcpf(1.0f + __expf(-g)); }
; DI void gatenorm_phase(PPtr p, int wave, int lane) {
;     ...
;     for (int t0 = gw * 2; t0 < T; t0 += ngw * 2) {
;         u32x4 yv[2][4], zv[2][4];
; #pragma unroll
;         for (int rr = 0; rr < 2; ++rr)
; #pragma unroll
;             for (int jg = 0; jg < 4; ++jg) { const int c = 8 * (lane + 64 * jg);
;                 yv[rr][jg] = *(const u32x4*)(Y + (size_t)(t0 + rr) * DIN + c); zv[rr][jg] = *(const u32x4*)(zx + (size_t)(t0 + rr) * ZXW + c); }
; #pragma unroll
;         for (int rr = 0; rr < 2; ++rr)
; #pragma unroll
;             for (int jg = 0; jg < 4; ++jg) {
;                 const int c = 8 * (lane + 64 * jg);
;                 float v[8]; float ss = 0.f;
; #pragma unroll
;                 for (int i = 0; i < 4; ++i) { v[2 * i] = bflo(yv[rr][jg][i]) * silu_f(bflo(zv[rr][jg][i])); v[2 * i + 1] = bfhi(yv[rr][jg][i]) * silu_f(bfhi(zv[rr][jg][i])); ss += v[2 * i] * v[2 * i] + v[2 * i + 1] * v[2 * i + 1]; }
.LBB0_727:
	v_lshl_add_u64 v[56:57], s[10:11], 0, v[0:1]
	v_add_co_u32_e32 v2, vcc, 0x1e440000, v56
	v_lshl_add_u64 v[4:5], s[8:9], 0, v[0:1]
	s_nop 0
	v_addc_co_u32_e32 v3, vcc, 0, v57, vcc
	global_load_dwordx4 v[50:53], v[2:3], off
	v_add_co_u32_e32 v6, vcc, s1, v4
	s_mov_b32 s0, 0x1e441000
	s_nop 0
	v_addc_co_u32_e32 v7, vcc, 0, v5, vcc
	global_load_dwordx4 v[58:61], v[6:7], off
	global_load_dwordx4 v[78:81], v[2:3], off offset:1024
	global_load_dwordx4 v[82:85], v[6:7], off offset:1024
	global_load_dwordx4 v[42:45], v[2:3], off offset:2048
	global_load_dwordx4 v[46:49], v[6:7], off offset:2048
	global_load_dwordx4 v[34:37], v[2:3], off offset:3072
	global_load_dwordx4 v[38:41], v[6:7], off offset:3072
	v_add_co_u32_e32 v2, vcc, s0, v56
	s_mov_b32 s0, 0xd242000
	s_nop 0
	v_addc_co_u32_e32 v3, vcc, 0, v57, vcc
	v_add_co_u32_e32 v6, vcc, s0, v4
	s_mov_b32 s0, 0xd243000
	s_nop 0
	v_addc_co_u32_e32 v7, vcc, 0, v5, vcc
	global_load_dwordx4 v[26:29], v[2:3], off
	global_load_dwordx4 v[30:33], v[6:7], off offset:2048
	global_load_dwordx4 v[18:21], v[2:3], off offset:1024
	global_load_dwordx4 v[22:25], v[6:7], off offset:3072
	global_load_dwordx4 v[10:13], v[2:3], off offset:2048
	v_add_co_u32_e32 v6, vcc, s0, v4
	s_mov_b32 s0, 0x358637bd
	s_nop 0
	v_addc_co_u32_e32 v7, vcc, 0, v5, vcc
	global_load_dwordx4 v[14:17], v[6:7], off
	s_nop 0
	global_load_dwordx4 v[2:5], v[2:3], off offset:3072
	s_nop 0
	global_load_dwordx4 v[6:9], v[6:7], off offset:1024
	s_add_i32 s6, s6, s2
	s_waitcnt vmcnt(14)
	v_lshlrev_b32_e32 v54, 16, v61
	v_and_b32_e32 v55, 0xffff0000, v61
	v_mul_f32_e32 v61, 0xbfb8aa3b, v54
	v_lshlrev_b32_e32 v64, 16, v53
	v_and_b32_e32 v65, 0xffff0000, v53
	v_mul_f32_e32 v53, 0xbfb8aa3b, v55
	v_exp_f32_e32 v61, v61
	v_exp_f32_e32 v53, v53
	v_add_f32_e32 v61, 1.0, v61
	v_add_f32_e32 v53, 1.0, v53
	v_rcp_f32_e32 v62, v61
	v_rcp_f32_e32 v63, v53
	s_nop 0
	v_pk_mul_f32 v[54:55], v[62:63], v[54:55]
	s_nop 0
	v_pk_mul_f32 v[66:67], v[54:55], v[64:65]
	v_lshlrev_b32_e32 v54, 16, v60
	v_and_b32_e32 v55, 0xffff0000, v60
	v_mul_f32_e32 v53, 0xbfb8aa3b, v54
	v_lshlrev_b32_e32 v62, 16, v52
	v_and_b32_e32 v63, 0xffff0000, v52
	v_mul_f32_e32 v52, 0xbfb8aa3b, v55
	v_exp_f32_e32 v53, v53
	v_exp_f32_e32 v52, v52
	v_lshlrev_b32_e32 v64, 16, v51
	v_and_b32_e32 v65, 0xffff0000, v51
	v_add_f32_e32 v53, 1.0, v53
	v_add_f32_e32 v52, 1.0, v52
	v_rcp_f32_e32 v60, v53
	v_rcp_f32_e32 v61, v52
	s_nop 0
	v_pk_mul_f32 v[52:53], v[60:61], v[54:55]
	s_nop 0
	v_pk_mul_f32 v[52:53], v[52:53], v[62:63]
	v_mov_b32_e32 v54, v66
	v_mov_b32_e32 v55, v52
	v_pk_mul_f32 v[54:55], v[54:55], v[54:55]
	v_mov_b32_e32 v60, v67
	v_mov_b32_e32 v61, v53
	v_pk_fma_f32 v[54:55], v[60:61], v[60:61], v[54:55]
	v_lshlrev_b32_e32 v60, 16, v59
	v_and_b32_e32 v61, 0xffff0000, v59
	v_mul_f32_e32 v59, 0xbfb8aa3b, v60
	v_mul_f32_e32 v51, 0xbfb8aa3b, v61
	v_exp_f32_e32 v59, v59
	v_exp_f32_e32 v51, v51
	v_add_f32_e32 v59, 1.0, v59
	v_add_f32_e32 v51, 1.0, v51
	v_rcp_f32_e32 v62, v59
	v_rcp_f32_e32 v63, v51
	s_nop 0
	v_pk_mul_f32 v[60:61], v[62:63], v[60:61]
	s_nop 0
	v_pk_mul_f32 v[70:71], v[60:61], v[64:65]
	v_lshlrev_b32_e32 v60, 16, v58
	v_and_b32_e32 v61, 0xffff0000, v58
	v_mul_f32_e32 v51, 0xbfb8aa3b, v60
	v_lshlrev_b32_e32 v62, 16, v50
	v_and_b32_e32 v63, 0xffff0000, v50
	v_mul_f32_e32 v50, 0xbfb8aa3b, v61
	v_exp_f32_e32 v51, v51
	v_exp_f32_e32 v50, v50
	s_waitcnt vmcnt(13)
	v_lshlrev_b32_e32 v64, 16, v80
	v_and_b32_e32 v65, 0xffff0000, v80
	v_add_f32_e32 v51, 1.0, v51
	v_add_f32_e32 v50, 1.0, v50
	v_rcp_f32_e32 v58, v51
	v_rcp_f32_e32 v59, v50
	s_nop 0
	v_pk_mul_f32 v[50:51], v[58:59], v[60:61]
	s_nop 0
	v_pk_mul_f32 v[50:51], v[50:51], v[62:63]
	v_mov_b32_e32 v59, v70
	v_mov_b32_e32 v58, v50
	v_pk_mul_f32 v[58:59], v[58:59], v[58:59]
	v_mov_b32_e32 v60, v51
	v_mov_b32_e32 v61, v71
	v_pk_fma_f32 v[68:69], v[60:61], v[60:61], v[58:59]
	s_waitcnt vmcnt(12)
	v_lshlrev_b32_e32 v58, 16, v85
	v_and_b32_e32 v59, 0xffff0000, v85
	v_mul_f32_e32 v60, 0xbfb8aa3b, v58
	v_mul_f32_e32 v61, 0xbfb8aa3b, v59
	v_exp_f32_e32 v60, v60
	v_exp_f32_e32 v61, v61
	v_lshlrev_b32_e32 v62, 16, v81
	v_and_b32_e32 v63, 0xffff0000, v81
	v_add_f32_e32 v60, 1.0, v60
	v_add_f32_e32 v61, 1.0, v61
	v_rcp_f32_e32 v60, v60
	v_rcp_f32_e32 v61, v61
	v_and_b32_e32 v85, 0xffff0000, v79
	v_pk_mul_f32 v[58:59], v[60:61], v[58:59]
	v_lshlrev_b32_e32 v60, 16, v84
	v_and_b32_e32 v61, 0xffff0000, v84
	v_pk_mul_f32 v[58:59], v[58:59], v[62:63]
	v_mul_f32_e32 v62, 0xbfb8aa3b, v60
	v_mul_f32_e32 v63, 0xbfb8aa3b, v61
	v_exp_f32_e32 v62, v62
	v_exp_f32_e32 v63, v63
	v_lshlrev_b32_e32 v84, 16, v79
	v_add_f32_e32 v62, 1.0, v62
	v_add_f32_e32 v63, 1.0, v63
	v_rcp_f32_e32 v62, v62
	v_rcp_f32_e32 v63, v63
	s_nop 0
	v_pk_mul_f32 v[60:61], v[62:63], v[60:61]
	s_nop 0
	v_pk_mul_f32 v[60:61], v[60:61], v[64:65]
	v_mov_b32_e32 v62, v58
	v_mov_b32_e32 v63, v60
	v_pk_mul_f32 v[62:63], v[62:63], v[62:63]
	v_mov_b32_e32 v64, v59
	v_mov_b32_e32 v65, v61
	v_pk_fma_f32 v[80:81], v[64:65], v[64:65], v[62:63]
	v_lshlrev_b32_e32 v62, 16, v83
	v_and_b32_e32 v63, 0xffff0000, v83
	v_mul_f32_e32 v64, 0xbfb8aa3b, v62
	v_mul_f32_e32 v65, 0xbfb8aa3b, v63
	v_exp_f32_e32 v64, v64
	v_exp_f32_e32 v65, v65
	v_add_f32_e32 v64, 1.0, v64
	v_add_f32_e32 v65, 1.0, v65
	v_rcp_f32_e32 v64, v64
	v_rcp_f32_e32 v65, v65
	s_nop 0
	v_pk_mul_f32 v[62:63], v[64:65], v[62:63]
	v_lshlrev_b32_e32 v64, 16, v82
	v_and_b32_e32 v65, 0xffff0000, v82
	v_pk_mul_f32 v[62:63], v[62:63], v[84:85]
	v_mul_f32_e32 v79, 0xbfb8aa3b, v64
	v_lshlrev_b32_e32 v84, 16, v78
	v_and_b32_e32 v85, 0xffff0000, v78
	v_mul_f32_e32 v78, 0xbfb8aa3b, v65
	v_exp_f32_e32 v79, v79
	v_exp_f32_e32 v78, v78
	v_add_f32_e32 v79, 1.0, v79
; DI unsigned pk2(float lo, float hi) { f32x2 v = {lo, hi}; bf16x2_t b = __builtin_convertvector(v, bf16x2_t); return __builtin_bit_cast(unsigned, b); }
; DI void gatenorm_phase(PPtr p, int wave, int lane) {
;     ...
;                 const float rs = rsqrtf(wave_sum(ss) * (1.0f / 512.0f) + EPS);
;                 u32x4 w;
; #pragma unroll
;                 for (int i = 0; i < 4; ++i) w[i] = pk2(v[2 * i] * rs, v[2 * i + 1] * rs);
;                 *(u32x4*)(gn + (size_t)(t0 + rr) * DIN + c) = w;
	v_add_f32_e32 v78, 1.0, v78
	v_rcp_f32_e32 v82, v79
	v_rcp_f32_e32 v83, v78
	v_mov_b32_e32 v79, v62
	v_pk_mul_f32 v[64:65], v[82:83], v[64:65]
	s_nop 0
	v_pk_mul_f32 v[64:65], v[64:65], v[84:85]
	v_mov_b32_e32 v83, v63
	v_mov_b32_e32 v78, v64
	v_pk_mul_f32 v[78:79], v[78:79], v[78:79]
	v_mov_b32_e32 v82, v65
	v_pk_fma_f32 v[78:79], v[82:83], v[82:83], v[78:79]
	v_mov_b32_e32 v83, v68
	v_mov_b32_e32 v82, v78
	v_mov_b32_e32 v68, v79
	v_pk_add_f32 v[68:69], v[82:83], v[68:69]
	v_mov_b32_e32 v78, v81
	v_mov_b32_e32 v79, v55
	v_pk_add_f32 v[68:69], v[78:79], v[68:69]
	v_mov_b32_e32 v81, v54
	v_pk_add_f32 v[54:55], v[80:81], v[68:69]
	s_nop 1
	v_add_f32_dpp v54, v54, v54 row_shr:1 row_mask:0xf bank_mask:0xf bound_ctrl:0
	v_add_f32_dpp v55, v55, v55 row_shr:1 row_mask:0xf bank_mask:0xf bound_ctrl:0
	s_nop 0
	v_add_f32_dpp v54, v54, v54 row_shr:2 row_mask:0xf bank_mask:0xf bound_ctrl:0
	v_add_f32_dpp v55, v55, v55 row_shr:2 row_mask:0xf bank_mask:0xf bound_ctrl:0
	s_nop 0
	v_add_f32_dpp v54, v54, v54 row_shr:4 row_mask:0xf bank_mask:0xf bound_ctrl:0
	v_add_f32_dpp v55, v55, v55 row_shr:4 row_mask:0xf bank_mask:0xf bound_ctrl:0
	s_nop 0
	v_add_f32_dpp v54, v54, v54 row_shr:8 row_mask:0xf bank_mask:0xf bound_ctrl:0
	v_add_f32_dpp v55, v55, v55 row_shr:8 row_mask:0xf bank_mask:0xf bound_ctrl:0
	s_nop 0
	v_add_f32_dpp v54, v54, v54 row_bcast:15 row_mask:0xa bank_mask:0xf
	v_add_f32_dpp v55, v55, v55 row_bcast:15 row_mask:0xa bank_mask:0xf
	s_nop 0
	v_add_f32_dpp v54, v54, v54 row_bcast:31 row_mask:0xc bank_mask:0xf
	v_add_f32_dpp v55, v55, v55 row_bcast:31 row_mask:0xc bank_mask:0xf
	s_nop 0
	v_readlane_b32 s24, v54, 63
	v_readlane_b32 s25, v55, 63
	s_nop 1
	v_mov_b32_e32 v68, s24
	v_mov_b32_e32 v69, s25
	v_mov_b64_e32 v[54:55], s[0:1]
	v_pk_fma_f32 v[68:69], v[68:69], s[14:15], v[54:55] op_sel_hi:[1,0,0]
	s_mov_b32 s0, 0x17441000
	v_mul_f32_e32 v78, 0x4b800000, v69
	v_cmp_gt_f32_e64 s[4:5], s91, v69
	v_cmp_gt_f32_e32 vcc, s91, v68
	s_nop 0
	v_cndmask_b32_e64 v69, v69, v78, s[4:5]
	v_rsq_f32_e32 v69, v69
	s_nop 0
	v_mul_f32_e32 v78, 0x45800000, v69
	v_cndmask_b32_e64 v78, v69, v78, s[4:5]
	v_pk_mul_f32 v[52:53], v[52:53], v[78:79] op_sel_hi:[1,0]
	v_pk_mul_f32 v[66:67], v[66:67], v[78:79] op_sel_hi:[1,0]
	v_cvt_pk_bf16_f32 v52, v52, v53
	v_cvt_pk_bf16_f32 v53, v66, v67
	v_add_co_u32_e64 v66, s[4:5], s3, v56
	v_pk_mul_f32 v[50:51], v[50:51], v[78:79] op_sel_hi:[1,0]
	s_nop 0
	v_addc_co_u32_e64 v67, s[4:5], 0, v57, s[4:5]
	v_pk_mul_f32 v[70:71], v[70:71], v[78:79] op_sel_hi:[1,0]
	v_add_co_u32_e64 v56, s[4:5], s0, v56
	v_cvt_pk_bf16_f32 v50, v50, v51
	v_cvt_pk_bf16_f32 v51, v70, v71
	v_addc_co_u32_e64 v57, s[4:5], 0, v57, s[4:5]
	global_store_dwordx4 v[56:57], v[50:53], off offset:-4096
	s_mul_i32 s0, s90, 0x28000
	s_add_u32 s8, s8, s0
	v_mul_f32_e32 v50, 0x4b800000, v68
	v_cndmask_b32_e32 v50, v68, v50, vcc
	v_rsq_f32_e32 v50, v50
	s_mul_hi_i32 s0, s2, 0x2800
	s_addc_u32 s9, s9, s0
	s_add_u32 s10, s10, s12
	v_mul_f32_e32 v51, 0x45800000, v50
	v_cndmask_b32_e32 v68, v50, v51, vcc
	v_pk_mul_f32 v[50:51], v[64:65], v[68:69] op_sel_hi:[1,0]
	v_pk_mul_f32 v[52:53], v[62:63], v[68:69] op_sel_hi:[1,0]
	v_cvt_pk_bf16_f32 v50, v50, v51
	v_cvt_pk_bf16_f32 v51, v52, v53
	v_pk_mul_f32 v[52:53], v[60:61], v[68:69] op_sel_hi:[1,0]
	v_pk_mul_f32 v[58:59], v[58:59], v[68:69] op_sel_hi:[1,0]
	v_cvt_pk_bf16_f32 v52, v52, v53
	v_cvt_pk_bf16_f32 v53, v58, v59
	global_store_dwordx4 v[66:67], v[50:53], off offset:1024
	s_waitcnt vmcnt(13)
	v_lshlrev_b32_e32 v58, 16, v45
	v_and_b32_e32 v59, 0xffff0000, v45
	s_waitcnt vmcnt(12)
	v_lshlrev_b32_e32 v50, 16, v49
	v_and_b32_e32 v51, 0xffff0000, v49
	v_mul_f32_e32 v49, 0xbfb8aa3b, v50
	v_mul_f32_e32 v45, 0xbfb8aa3b, v51
	v_exp_f32_e32 v49, v49
	v_exp_f32_e32 v45, v45
	v_lshlrev_b32_e32 v60, 16, v43
	v_and_b32_e32 v61, 0xffff0000, v43
	v_add_f32_e32 v49, 1.0, v49
	v_add_f32_e32 v45, 1.0, v45
	v_rcp_f32_e32 v52, v49
	v_rcp_f32_e32 v53, v45
	s_waitcnt vmcnt(11)
	v_lshlrev_b32_e32 v62, 16, v37
	v_and_b32_e32 v63, 0xffff0000, v37
	v_lshlrev_b32_e32 v64, 16, v35
	v_pk_mul_f32 v[50:51], v[52:53], v[50:51]
	v_lshlrev_b32_e32 v52, 16, v48
	v_and_b32_e32 v53, 0xffff0000, v48
	v_pk_mul_f32 v[50:51], v[50:51], v[58:59]
	v_mul_f32_e32 v45, 0xbfb8aa3b, v52
	v_lshlrev_b32_e32 v58, 16, v44
	v_and_b32_e32 v59, 0xffff0000, v44
	v_mul_f32_e32 v44, 0xbfb8aa3b, v53
	v_exp_f32_e32 v45, v45
	v_exp_f32_e32 v44, v44
	v_and_b32_e32 v65, 0xffff0000, v35
	s_addc_u32 s11, s11, s13
	v_add_f32_e32 v45, 1.0, v45
	v_add_f32_e32 v44, 1.0, v44
	v_rcp_f32_e32 v48, v45
	v_rcp_f32_e32 v49, v44
	s_cmpk_lt_i32 s6, 0x4000
	v_pk_mul_f32 v[44:45], v[48:49], v[52:53]
	s_nop 0
	v_pk_mul_f32 v[44:45], v[44:45], v[58:59]
	v_mov_b32_e32 v48, v50
	v_mov_b32_e32 v49, v44
	v_pk_mul_f32 v[48:49], v[48:49], v[48:49]
	v_mov_b32_e32 v52, v51
	v_mov_b32_e32 v53, v45
	v_pk_fma_f32 v[48:49], v[52:53], v[52:53], v[48:49]
	v_lshlrev_b32_e32 v52, 16, v47
	v_and_b32_e32 v53, 0xffff0000, v47
	v_mul_f32_e32 v47, 0xbfb8aa3b, v52
	v_mul_f32_e32 v43, 0xbfb8aa3b, v53
	v_exp_f32_e32 v47, v47
	v_exp_f32_e32 v43, v43
	v_add_f32_e32 v47, 1.0, v47
	v_add_f32_e32 v43, 1.0, v43
	v_rcp_f32_e32 v58, v47
	v_rcp_f32_e32 v59, v43
	s_nop 0
	v_pk_mul_f32 v[52:53], v[58:59], v[52:53]
	v_lshlrev_b32_e32 v58, 16, v46
	v_and_b32_e32 v59, 0xffff0000, v46
	v_pk_mul_f32 v[52:53], v[52:53], v[60:61]
	v_mul_f32_e32 v43, 0xbfb8aa3b, v58
	v_lshlrev_b32_e32 v60, 16, v42
	v_and_b32_e32 v61, 0xffff0000, v42
	v_mul_f32_e32 v42, 0xbfb8aa3b, v59
	v_exp_f32_e32 v43, v43
	v_exp_f32_e32 v42, v42
	v_add_f32_e32 v43, 1.0, v43
	v_add_f32_e32 v42, 1.0, v42
	v_rcp_f32_e32 v46, v43
	v_rcp_f32_e32 v47, v42
	s_nop 0
	v_pk_mul_f32 v[42:43], v[46:47], v[58:59]
	s_nop 0
	v_pk_mul_f32 v[42:43], v[42:43], v[60:61]
	v_mov_b32_e32 v47, v52
	v_mov_b32_e32 v46, v42
	v_pk_mul_f32 v[46:47], v[46:47], v[46:47]
	v_mov_b32_e32 v58, v43
	v_mov_b32_e32 v59, v53
	v_pk_fma_f32 v[46:47], v[58:59], v[58:59], v[46:47]
	s_waitcnt vmcnt(10)
; DI unsigned pk2(float lo, float hi) { f32x2 v = {lo, hi}; bf16x2_t b = __builtin_convertvector(v, bf16x2_t); return __builtin_bit_cast(unsigned, b); }
; DI float bflo(unsigned w) { return __uint_as_float(w << 16); }
; DI float bfhi(unsigned w) { return __uint_as_float(w & 0xffff0000u); }
; DI float silu_f(float g) { return g * __builtin_amdgcn_rcpf(1.0f + __expf(-g)); }
; DI void gatenorm_phase(PPtr p, int wave, int lane) {
;     ...
;                 for (int i = 0; i < 4; ++i) { v[2 * i] = bflo(yv[rr][jg][i]) * silu_f(bflo(zv[rr][jg][i])); v[2 * i + 1] = bfhi(yv[rr][jg][i]) * silu_f(bfhi(zv[rr][jg][i])); ss += v[2 * i] * v[2 * i] + v[2 * i + 1] * v[2 * i + 1]; }
;                 const float rs = rsqrtf(wave_sum(ss) * (1.0f / 512.0f) + EPS);
;                 u32x4 w;
; #pragma unroll
;                 for (int i = 0; i < 4; ++i) w[i] = pk2(v[2 * i] * rs, v[2 * i + 1] * rs);
;                 *(u32x4*)(gn + (size_t)(t0 + rr) * DIN + c) = w;
	v_lshlrev_b32_e32 v58, 16, v41
	v_and_b32_e32 v59, 0xffff0000, v41
	v_mul_f32_e32 v41, 0xbfb8aa3b, v58
	v_mul_f32_e32 v37, 0xbfb8aa3b, v59
	v_exp_f32_e32 v41, v41
	v_exp_f32_e32 v37, v37
	v_add_f32_e32 v41, 1.0, v41
	v_add_f32_e32 v37, 1.0, v37
	v_rcp_f32_e32 v60, v41
	v_rcp_f32_e32 v61, v37
	s_nop 0
	v_pk_mul_f32 v[58:59], v[60:61], v[58:59]
	v_lshlrev_b32_e32 v60, 16, v40
	v_and_b32_e32 v61, 0xffff0000, v40
	v_pk_mul_f32 v[58:59], v[58:59], v[62:63]
	v_mul_f32_e32 v37, 0xbfb8aa3b, v60
	v_lshlrev_b32_e32 v62, 16, v36
	v_and_b32_e32 v63, 0xffff0000, v36
	v_mul_f32_e32 v36, 0xbfb8aa3b, v61
	v_exp_f32_e32 v37, v37
	v_exp_f32_e32 v36, v36
	v_add_f32_e32 v37, 1.0, v37
	v_add_f32_e32 v36, 1.0, v36
	v_rcp_f32_e32 v40, v37
	v_rcp_f32_e32 v41, v36
	s_nop 0
	v_pk_mul_f32 v[36:37], v[40:41], v[60:61]
	s_nop 0
	v_pk_mul_f32 v[40:41], v[36:37], v[62:63]
	v_mov_b32_e32 v36, v58
	v_mov_b32_e32 v37, v40
	v_pk_mul_f32 v[36:37], v[36:37], v[36:37]
	v_mov_b32_e32 v60, v59
	v_mov_b32_e32 v61, v41
	v_pk_fma_f32 v[36:37], v[60:61], v[60:61], v[36:37]
	v_lshlrev_b32_e32 v60, 16, v39
	v_and_b32_e32 v61, 0xffff0000, v39
	v_mul_f32_e32 v39, 0xbfb8aa3b, v60
	v_mul_f32_e32 v35, 0xbfb8aa3b, v61
	v_exp_f32_e32 v39, v39
	v_exp_f32_e32 v35, v35
	v_add_f32_e32 v39, 1.0, v39
	v_add_f32_e32 v35, 1.0, v35
	v_rcp_f32_e32 v62, v39
	v_rcp_f32_e32 v63, v35
	s_nop 0
	v_pk_mul_f32 v[60:61], v[62:63], v[60:61]
	v_lshlrev_b32_e32 v62, 16, v38
	v_and_b32_e32 v63, 0xffff0000, v38
	v_pk_mul_f32 v[60:61], v[60:61], v[64:65]
	v_mul_f32_e32 v35, 0xbfb8aa3b, v62
	v_lshlrev_b32_e32 v64, 16, v34
	v_and_b32_e32 v65, 0xffff0000, v34
	v_mul_f32_e32 v34, 0xbfb8aa3b, v63
	v_exp_f32_e32 v35, v35
	v_exp_f32_e32 v34, v34
	v_add_f32_e32 v35, 1.0, v35
	v_add_f32_e32 v34, 1.0, v34
	v_rcp_f32_e32 v38, v35
	v_rcp_f32_e32 v39, v34
	s_nop 0
	v_pk_mul_f32 v[34:35], v[38:39], v[62:63]
	s_nop 0
	v_pk_mul_f32 v[38:39], v[34:35], v[64:65]
	v_mov_b32_e32 v35, v60
	v_mov_b32_e32 v34, v38
	v_pk_mul_f32 v[34:35], v[34:35], v[34:35]
	v_mov_b32_e32 v62, v39
	v_mov_b32_e32 v63, v61
	v_pk_fma_f32 v[34:35], v[62:63], v[62:63], v[34:35]
	v_mov_b32_e32 v63, v46
	v_mov_b32_e32 v62, v34
	v_mov_b32_e32 v46, v35
	v_pk_add_f32 v[34:35], v[62:63], v[46:47]
	v_mov_b32_e32 v46, v37
	v_mov_b32_e32 v47, v49
	v_pk_add_f32 v[34:35], v[46:47], v[34:35]
	v_mov_b32_e32 v37, v48
	v_pk_add_f32 v[34:35], v[36:37], v[34:35]
	s_nop 1
	v_add_f32_dpp v34, v34, v34 row_shr:1 row_mask:0xf bank_mask:0xf bound_ctrl:0
	v_add_f32_dpp v35, v35, v35 row_shr:1 row_mask:0xf bank_mask:0xf bound_ctrl:0
	s_nop 0
	v_add_f32_dpp v34, v34, v34 row_shr:2 row_mask:0xf bank_mask:0xf bound_ctrl:0
	v_add_f32_dpp v35, v35, v35 row_shr:2 row_mask:0xf bank_mask:0xf bound_ctrl:0
	s_nop 0
	v_add_f32_dpp v34, v34, v34 row_shr:4 row_mask:0xf bank_mask:0xf bound_ctrl:0
	v_add_f32_dpp v35, v35, v35 row_shr:4 row_mask:0xf bank_mask:0xf bound_ctrl:0
	s_nop 0
	v_add_f32_dpp v34, v34, v34 row_shr:8 row_mask:0xf bank_mask:0xf bound_ctrl:0
	v_add_f32_dpp v35, v35, v35 row_shr:8 row_mask:0xf bank_mask:0xf bound_ctrl:0
	s_nop 0
	v_add_f32_dpp v34, v34, v34 row_bcast:15 row_mask:0xa bank_mask:0xf
	v_add_f32_dpp v35, v35, v35 row_bcast:15 row_mask:0xa bank_mask:0xf
	s_nop 0
	v_add_f32_dpp v34, v34, v34 row_bcast:31 row_mask:0xc bank_mask:0xf
	v_add_f32_dpp v35, v35, v35 row_bcast:31 row_mask:0xc bank_mask:0xf
	s_nop 0
	v_readlane_b32 s24, v34, 63
	v_readlane_b32 s25, v35, 63
	s_nop 1
	v_mov_b32_e32 v34, s24
	v_mov_b32_e32 v35, s25
	s_nop 0
	v_pk_fma_f32 v[46:47], v[34:35], s[14:15], v[54:55] op_sel_hi:[1,0,0]
	s_nop 0
	v_mul_f32_e32 v34, 0x4b800000, v47
	v_cmp_gt_f32_e64 s[4:5], s91, v47
	v_cmp_gt_f32_e32 vcc, s91, v46
	s_nop 0
	v_cndmask_b32_e64 v34, v47, v34, s[4:5]
	v_rsq_f32_e32 v34, v34
	s_nop 0
	v_mul_f32_e32 v35, 0x45800000, v34
	v_cndmask_b32_e64 v48, v34, v35, s[4:5]
	v_pk_mul_f32 v[34:35], v[42:43], v[48:49] op_sel_hi:[1,0]
	v_pk_mul_f32 v[36:37], v[52:53], v[48:49] op_sel_hi:[1,0]
	v_cvt_pk_bf16_f32 v34, v34, v35
	v_cvt_pk_bf16_f32 v35, v36, v37
	v_pk_mul_f32 v[36:37], v[44:45], v[48:49] op_sel_hi:[1,0]
	v_pk_mul_f32 v[42:43], v[50:51], v[48:49] op_sel_hi:[1,0]
	v_cvt_pk_bf16_f32 v36, v36, v37
	v_cvt_pk_bf16_f32 v37, v42, v43
	global_store_dwordx4 v[66:67], v[34:37], off offset:2048
	s_waitcnt vmcnt(8)
; DI unsigned pk2(float lo, float hi) { f32x2 v = {lo, hi}; bf16x2_t b = __builtin_convertvector(v, bf16x2_t); return __builtin_bit_cast(unsigned, b); }
; DI float bflo(unsigned w) { return __uint_as_float(w << 16); }
; DI float bfhi(unsigned w) { return __uint_as_float(w & 0xffff0000u); }
; DI float silu_f(float g) { return g * __builtin_amdgcn_rcpf(1.0f + __expf(-g)); }
; DI void gatenorm_phase(PPtr p, int wave, int lane) {
;     ...
;                 for (int i = 0; i < 4; ++i) { v[2 * i] = bflo(yv[rr][jg][i]) * silu_f(bflo(zv[rr][jg][i])); v[2 * i + 1] = bfhi(yv[rr][jg][i]) * silu_f(bfhi(zv[rr][jg][i])); ss += v[2 * i] * v[2 * i] + v[2 * i + 1] * v[2 * i + 1]; }
;                 const float rs = rsqrtf(wave_sum(ss) * (1.0f / 512.0f) + EPS);
;                 u32x4 w;
; #pragma unroll
;                 for (int i = 0; i < 4; ++i) w[i] = pk2(v[2 * i] * rs, v[2 * i + 1] * rs);
;                 *(u32x4*)(gn + (size_t)(t0 + rr) * DIN + c) = w;
	v_lshlrev_b32_e32 v44, 16, v19
	v_and_b32_e32 v45, 0xffff0000, v19
	v_mul_f32_e32 v34, 0x4b800000, v46
	v_cndmask_b32_e32 v34, v46, v34, vcc
	v_rsq_f32_e32 v34, v34
	s_nop 0
	v_mul_f32_e32 v35, 0x45800000, v34
	v_cndmask_b32_e32 v42, v34, v35, vcc
	v_pk_mul_f32 v[34:35], v[38:39], v[42:43] op_sel_hi:[1,0]
	v_pk_mul_f32 v[36:37], v[60:61], v[42:43] op_sel_hi:[1,0]
	v_cvt_pk_bf16_f32 v34, v34, v35
	v_cvt_pk_bf16_f32 v35, v36, v37
	v_pk_mul_f32 v[36:37], v[40:41], v[42:43] op_sel_hi:[1,0]
	v_pk_mul_f32 v[38:39], v[58:59], v[42:43] op_sel_hi:[1,0]
	v_cvt_pk_bf16_f32 v36, v36, v37
	v_cvt_pk_bf16_f32 v37, v38, v39
	global_store_dwordx4 v[66:67], v[34:37], off offset:3072
	v_lshlrev_b32_e32 v38, 16, v29
	v_and_b32_e32 v39, 0xffff0000, v29
	v_lshlrev_b32_e32 v34, 16, v33
	v_and_b32_e32 v35, 0xffff0000, v33
	v_mul_f32_e32 v33, 0xbfb8aa3b, v34
	v_mul_f32_e32 v29, 0xbfb8aa3b, v35
	v_exp_f32_e32 v33, v33
	v_exp_f32_e32 v29, v29
	v_lshlrev_b32_e32 v40, 16, v27
	v_and_b32_e32 v41, 0xffff0000, v27
	v_add_f32_e32 v33, 1.0, v33
	v_add_f32_e32 v29, 1.0, v29
	v_rcp_f32_e32 v36, v33
	v_rcp_f32_e32 v37, v29
	v_lshlrev_b32_e32 v42, 16, v21
	v_and_b32_e32 v43, 0xffff0000, v21
	v_pk_mul_f32 v[34:35], v[36:37], v[34:35]
	v_lshlrev_b32_e32 v36, 16, v32
	v_and_b32_e32 v37, 0xffff0000, v32
	v_pk_mul_f32 v[34:35], v[34:35], v[38:39]
	v_mul_f32_e32 v29, 0xbfb8aa3b, v36
	v_lshlrev_b32_e32 v38, 16, v28
	v_and_b32_e32 v39, 0xffff0000, v28
	v_mul_f32_e32 v28, 0xbfb8aa3b, v37
	v_exp_f32_e32 v29, v29
	v_exp_f32_e32 v28, v28
	v_add_f32_e32 v29, 1.0, v29
	v_add_f32_e32 v28, 1.0, v28
	v_rcp_f32_e32 v32, v29
	v_rcp_f32_e32 v33, v28
	s_nop 0
	v_pk_mul_f32 v[28:29], v[32:33], v[36:37]
	s_nop 0
	v_pk_mul_f32 v[28:29], v[28:29], v[38:39]
	v_mov_b32_e32 v32, v34
	v_mov_b32_e32 v33, v28
	v_pk_mul_f32 v[32:33], v[32:33], v[32:33]
	v_mov_b32_e32 v36, v35
	v_mov_b32_e32 v37, v29
	v_pk_fma_f32 v[32:33], v[36:37], v[36:37], v[32:33]
	v_lshlrev_b32_e32 v36, 16, v31
	v_and_b32_e32 v37, 0xffff0000, v31
	v_mul_f32_e32 v31, 0xbfb8aa3b, v36
	v_mul_f32_e32 v27, 0xbfb8aa3b, v37
	v_exp_f32_e32 v31, v31
	v_exp_f32_e32 v27, v27
	v_add_f32_e32 v31, 1.0, v31
	v_add_f32_e32 v27, 1.0, v27
	v_rcp_f32_e32 v38, v31
	v_rcp_f32_e32 v39, v27
	s_nop 0
	v_pk_mul_f32 v[36:37], v[38:39], v[36:37]
	v_lshlrev_b32_e32 v38, 16, v30
	v_and_b32_e32 v39, 0xffff0000, v30
	v_pk_mul_f32 v[36:37], v[36:37], v[40:41]
	v_mul_f32_e32 v27, 0xbfb8aa3b, v38
	v_lshlrev_b32_e32 v40, 16, v26
	v_and_b32_e32 v41, 0xffff0000, v26
	v_mul_f32_e32 v26, 0xbfb8aa3b, v39
	v_exp_f32_e32 v27, v27
	v_exp_f32_e32 v26, v26
	v_add_f32_e32 v27, 1.0, v27
	v_add_f32_e32 v26, 1.0, v26
	v_rcp_f32_e32 v30, v27
	v_rcp_f32_e32 v31, v26
	s_nop 0
	v_pk_mul_f32 v[26:27], v[30:31], v[38:39]
	s_nop 0
	v_pk_mul_f32 v[26:27], v[26:27], v[40:41]
	v_mov_b32_e32 v31, v36
	v_mov_b32_e32 v30, v26
	v_pk_mul_f32 v[30:31], v[30:31], v[30:31]
	v_mov_b32_e32 v38, v27
	v_mov_b32_e32 v39, v37
	v_pk_fma_f32 v[30:31], v[38:39], v[38:39], v[30:31]
	s_waitcnt vmcnt(8)
	v_lshlrev_b32_e32 v38, 16, v25
	v_and_b32_e32 v39, 0xffff0000, v25
	v_mul_f32_e32 v25, 0xbfb8aa3b, v38
	v_mul_f32_e32 v21, 0xbfb8aa3b, v39
	v_exp_f32_e32 v25, v25
	v_exp_f32_e32 v21, v21
	v_add_f32_e32 v25, 1.0, v25
	v_add_f32_e32 v21, 1.0, v21
	v_rcp_f32_e32 v40, v25
	v_rcp_f32_e32 v41, v21
	s_nop 0
	v_pk_mul_f32 v[38:39], v[40:41], v[38:39]
	v_lshlrev_b32_e32 v40, 16, v24
	v_and_b32_e32 v41, 0xffff0000, v24
	v_pk_mul_f32 v[38:39], v[38:39], v[42:43]
	v_mul_f32_e32 v21, 0xbfb8aa3b, v40
	v_lshlrev_b32_e32 v42, 16, v20
	v_and_b32_e32 v43, 0xffff0000, v20
	v_mul_f32_e32 v20, 0xbfb8aa3b, v41
	v_exp_f32_e32 v21, v21
	v_exp_f32_e32 v20, v20
	v_add_f32_e32 v21, 1.0, v21
	v_add_f32_e32 v20, 1.0, v20
	v_rcp_f32_e32 v24, v21
	v_rcp_f32_e32 v25, v20
	s_nop 0
	v_pk_mul_f32 v[20:21], v[24:25], v[40:41]
	s_nop 0
	v_pk_mul_f32 v[24:25], v[20:21], v[42:43]
	v_mov_b32_e32 v20, v38
	v_mov_b32_e32 v21, v24
	v_pk_mul_f32 v[20:21], v[20:21], v[20:21]
	v_mov_b32_e32 v40, v39
	v_mov_b32_e32 v41, v25
	v_pk_fma_f32 v[20:21], v[40:41], v[40:41], v[20:21]
	v_lshlrev_b32_e32 v40, 16, v23
	v_and_b32_e32 v41, 0xffff0000, v23
	v_mul_f32_e32 v23, 0xbfb8aa3b, v40
	v_mul_f32_e32 v19, 0xbfb8aa3b, v41
	v_exp_f32_e32 v23, v23
	v_exp_f32_e32 v19, v19
	v_add_f32_e32 v23, 1.0, v23
	v_add_f32_e32 v19, 1.0, v19
	v_rcp_f32_e32 v42, v23
	v_rcp_f32_e32 v43, v19
	s_nop 0
	v_pk_mul_f32 v[40:41], v[42:43], v[40:41]
	v_lshlrev_b32_e32 v42, 16, v22
	v_and_b32_e32 v43, 0xffff0000, v22
	v_pk_mul_f32 v[40:41], v[40:41], v[44:45]
	v_mul_f32_e32 v19, 0xbfb8aa3b, v42
	v_lshlrev_b32_e32 v44, 16, v18
	v_and_b32_e32 v45, 0xffff0000, v18
	v_mul_f32_e32 v18, 0xbfb8aa3b, v43
	v_exp_f32_e32 v19, v19
	v_exp_f32_e32 v18, v18
	v_add_f32_e32 v19, 1.0, v19
	v_add_f32_e32 v18, 1.0, v18
	v_rcp_f32_e32 v22, v19
	v_rcp_f32_e32 v23, v18
	s_nop 0
	v_pk_mul_f32 v[18:19], v[22:23], v[42:43]
	s_nop 0
	v_pk_mul_f32 v[22:23], v[18:19], v[44:45]
	v_mov_b32_e32 v19, v40
	v_mov_b32_e32 v18, v22
	v_pk_mul_f32 v[18:19], v[18:19], v[18:19]
	v_mov_b32_e32 v42, v23
	v_mov_b32_e32 v43, v41
	v_pk_fma_f32 v[18:19], v[42:43], v[42:43], v[18:19]
	v_mov_b32_e32 v43, v30
	v_mov_b32_e32 v42, v18
	v_mov_b32_e32 v30, v19
	v_pk_add_f32 v[18:19], v[42:43], v[30:31]
	v_mov_b32_e32 v30, v21
	v_mov_b32_e32 v31, v33
	v_pk_add_f32 v[18:19], v[30:31], v[18:19]
	v_mov_b32_e32 v21, v32
	v_pk_add_f32 v[18:19], v[20:21], v[18:19]
	s_nop 1
	v_add_f32_dpp v18, v18, v18 row_shr:1 row_mask:0xf bank_mask:0xf bound_ctrl:0
	v_add_f32_dpp v19, v19, v19 row_shr:1 row_mask:0xf bank_mask:0xf bound_ctrl:0
	s_nop 0
	v_add_f32_dpp v18, v18, v18 row_shr:2 row_mask:0xf bank_mask:0xf bound_ctrl:0
; DI unsigned pk2(float lo, float hi) { f32x2 v = {lo, hi}; bf16x2_t b = __builtin_convertvector(v, bf16x2_t); return __builtin_bit_cast(unsigned, b); }
; DI float bflo(unsigned w) { return __uint_as_float(w << 16); }
; DI float bfhi(unsigned w) { return __uint_as_float(w & 0xffff0000u); }
; DI float silu_f(float g) { return g * __builtin_amdgcn_rcpf(1.0f + __expf(-g)); }
; DI void gatenorm_phase(PPtr p, int wave, int lane) {
;     ...
;                 for (int i = 0; i < 4; ++i) { v[2 * i] = bflo(yv[rr][jg][i]) * silu_f(bflo(zv[rr][jg][i])); v[2 * i + 1] = bfhi(yv[rr][jg][i]) * silu_f(bfhi(zv[rr][jg][i])); ss += v[2 * i] * v[2 * i] + v[2 * i + 1] * v[2 * i + 1]; }
;                 const float rs = rsqrtf(wave_sum(ss) * (1.0f / 512.0f) + EPS);
;                 u32x4 w;
; #pragma unroll
;                 for (int i = 0; i < 4; ++i) w[i] = pk2(v[2 * i] * rs, v[2 * i + 1] * rs);
;                 *(u32x4*)(gn + (size_t)(t0 + rr) * DIN + c) = w;
	v_add_f32_dpp v19, v19, v19 row_shr:2 row_mask:0xf bank_mask:0xf bound_ctrl:0
	s_nop 0
	v_add_f32_dpp v18, v18, v18 row_shr:4 row_mask:0xf bank_mask:0xf bound_ctrl:0
	v_add_f32_dpp v19, v19, v19 row_shr:4 row_mask:0xf bank_mask:0xf bound_ctrl:0
	s_nop 0
	v_add_f32_dpp v18, v18, v18 row_shr:8 row_mask:0xf bank_mask:0xf bound_ctrl:0
	v_add_f32_dpp v19, v19, v19 row_shr:8 row_mask:0xf bank_mask:0xf bound_ctrl:0
	s_nop 0
	v_add_f32_dpp v18, v18, v18 row_bcast:15 row_mask:0xa bank_mask:0xf
	v_add_f32_dpp v19, v19, v19 row_bcast:15 row_mask:0xa bank_mask:0xf
	s_nop 0
	v_add_f32_dpp v18, v18, v18 row_bcast:31 row_mask:0xc bank_mask:0xf
	v_add_f32_dpp v19, v19, v19 row_bcast:31 row_mask:0xc bank_mask:0xf
	s_nop 0
	v_readlane_b32 s24, v18, 63
	v_readlane_b32 s25, v19, 63
	s_nop 1
	v_mov_b32_e32 v18, s24
	v_mov_b32_e32 v19, s25
	s_nop 0
	v_pk_fma_f32 v[30:31], v[18:19], s[14:15], v[54:55] op_sel_hi:[1,0,0]
	s_nop 0
	v_mul_f32_e32 v18, 0x4b800000, v31
	v_cmp_gt_f32_e64 s[4:5], s91, v31
	v_cmp_gt_f32_e32 vcc, s91, v30
	s_nop 0
	v_cndmask_b32_e64 v18, v31, v18, s[4:5]
	v_rsq_f32_e32 v18, v18
	s_nop 0
	v_mul_f32_e32 v19, 0x45800000, v18
	v_cndmask_b32_e64 v32, v18, v19, s[4:5]
	v_pk_mul_f32 v[18:19], v[26:27], v[32:33] op_sel_hi:[1,0]
	v_pk_mul_f32 v[20:21], v[36:37], v[32:33] op_sel_hi:[1,0]
	v_cvt_pk_bf16_f32 v18, v18, v19
	v_cvt_pk_bf16_f32 v19, v20, v21
	v_pk_mul_f32 v[20:21], v[28:29], v[32:33] op_sel_hi:[1,0]
	v_pk_mul_f32 v[26:27], v[34:35], v[32:33] op_sel_hi:[1,0]
	v_cvt_pk_bf16_f32 v20, v20, v21
	v_cvt_pk_bf16_f32 v21, v26, v27
	global_store_dwordx4 v[56:57], v[18:21], off
	s_waitcnt vmcnt(6)
	v_lshlrev_b32_e32 v28, 16, v3
	v_and_b32_e32 v29, 0xffff0000, v3
	v_mul_f32_e32 v18, 0x4b800000, v30
	v_cndmask_b32_e32 v18, v30, v18, vcc
	v_rsq_f32_e32 v18, v18
	s_nop 0
	v_mul_f32_e32 v19, 0x45800000, v18
	v_cndmask_b32_e32 v26, v18, v19, vcc
	v_pk_mul_f32 v[18:19], v[22:23], v[26:27] op_sel_hi:[1,0]
	v_pk_mul_f32 v[20:21], v[40:41], v[26:27] op_sel_hi:[1,0]
	v_cvt_pk_bf16_f32 v18, v18, v19
	v_cvt_pk_bf16_f32 v19, v20, v21
	v_pk_mul_f32 v[20:21], v[24:25], v[26:27] op_sel_hi:[1,0]
	v_pk_mul_f32 v[22:23], v[38:39], v[26:27] op_sel_hi:[1,0]
	v_cvt_pk_bf16_f32 v20, v20, v21
	v_cvt_pk_bf16_f32 v21, v22, v23
	global_store_dwordx4 v[56:57], v[18:21], off offset:1024
	v_lshlrev_b32_e32 v22, 16, v13
	v_and_b32_e32 v23, 0xffff0000, v13
	v_lshlrev_b32_e32 v18, 16, v17
	v_and_b32_e32 v19, 0xffff0000, v17
	v_mul_f32_e32 v17, 0xbfb8aa3b, v18
	v_mul_f32_e32 v13, 0xbfb8aa3b, v19
	v_exp_f32_e32 v17, v17
	v_exp_f32_e32 v13, v13
	v_lshlrev_b32_e32 v24, 16, v11
	v_and_b32_e32 v25, 0xffff0000, v11
	v_add_f32_e32 v17, 1.0, v17
	v_add_f32_e32 v13, 1.0, v13
	v_rcp_f32_e32 v20, v17
	v_rcp_f32_e32 v21, v13
	v_lshlrev_b32_e32 v26, 16, v5
	v_and_b32_e32 v27, 0xffff0000, v5
	v_pk_mul_f32 v[18:19], v[20:21], v[18:19]
	v_lshlrev_b32_e32 v20, 16, v16
	v_and_b32_e32 v21, 0xffff0000, v16
	v_pk_mul_f32 v[18:19], v[18:19], v[22:23]
	v_mul_f32_e32 v13, 0xbfb8aa3b, v20
	v_lshlrev_b32_e32 v22, 16, v12
	v_and_b32_e32 v23, 0xffff0000, v12
	v_mul_f32_e32 v12, 0xbfb8aa3b, v21
	v_exp_f32_e32 v13, v13
	v_exp_f32_e32 v12, v12
	v_add_f32_e32 v13, 1.0, v13
	v_add_f32_e32 v12, 1.0, v12
	v_rcp_f32_e32 v16, v13
	v_rcp_f32_e32 v17, v12
	s_nop 0
	v_pk_mul_f32 v[12:13], v[16:17], v[20:21]
	s_nop 0
	v_pk_mul_f32 v[12:13], v[12:13], v[22:23]
	v_mov_b32_e32 v16, v18
	v_mov_b32_e32 v17, v12
	v_pk_mul_f32 v[16:17], v[16:17], v[16:17]
	v_mov_b32_e32 v20, v19
	v_mov_b32_e32 v21, v13
	v_pk_fma_f32 v[16:17], v[20:21], v[20:21], v[16:17]
	v_lshlrev_b32_e32 v20, 16, v15
	v_and_b32_e32 v21, 0xffff0000, v15
	v_mul_f32_e32 v15, 0xbfb8aa3b, v20
	v_mul_f32_e32 v11, 0xbfb8aa3b, v21
	v_exp_f32_e32 v15, v15
	v_exp_f32_e32 v11, v11
	v_add_f32_e32 v15, 1.0, v15
	v_add_f32_e32 v11, 1.0, v11
	v_rcp_f32_e32 v22, v15
	v_rcp_f32_e32 v23, v11
	s_nop 0
	v_pk_mul_f32 v[20:21], v[22:23], v[20:21]
	v_lshlrev_b32_e32 v22, 16, v14
	v_and_b32_e32 v23, 0xffff0000, v14
	v_pk_mul_f32 v[20:21], v[20:21], v[24:25]
	v_mul_f32_e32 v11, 0xbfb8aa3b, v22
	v_lshlrev_b32_e32 v24, 16, v10
	v_and_b32_e32 v25, 0xffff0000, v10
	v_mul_f32_e32 v10, 0xbfb8aa3b, v23
	v_exp_f32_e32 v11, v11
	v_exp_f32_e32 v10, v10
	v_add_f32_e32 v11, 1.0, v11
	v_add_f32_e32 v10, 1.0, v10
	v_rcp_f32_e32 v14, v11
	v_rcp_f32_e32 v15, v10
	s_nop 0
	v_pk_mul_f32 v[10:11], v[14:15], v[22:23]
	s_nop 0
	v_pk_mul_f32 v[10:11], v[10:11], v[24:25]
	v_mov_b32_e32 v15, v20
	v_mov_b32_e32 v14, v10
	v_pk_mul_f32 v[14:15], v[14:15], v[14:15]
	v_mov_b32_e32 v22, v11
	v_mov_b32_e32 v23, v21
	v_pk_fma_f32 v[14:15], v[22:23], v[22:23], v[14:15]
	s_waitcnt vmcnt(6)
; DI unsigned pk2(float lo, float hi) { f32x2 v = {lo, hi}; bf16x2_t b = __builtin_convertvector(v, bf16x2_t); return __builtin_bit_cast(unsigned, b); }
; DI float bflo(unsigned w) { return __uint_as_float(w << 16); }
; DI float bfhi(unsigned w) { return __uint_as_float(w & 0xffff0000u); }
; DI float silu_f(float g) { return g * __builtin_amdgcn_rcpf(1.0f + __expf(-g)); }
; DI void gatenorm_phase(PPtr p, int wave, int lane) {
;     ...
;                 for (int i = 0; i < 4; ++i) { v[2 * i] = bflo(yv[rr][jg][i]) * silu_f(bflo(zv[rr][jg][i])); v[2 * i + 1] = bfhi(yv[rr][jg][i]) * silu_f(bfhi(zv[rr][jg][i])); ss += v[2 * i] * v[2 * i] + v[2 * i + 1] * v[2 * i + 1]; }
;                 const float rs = rsqrtf(wave_sum(ss) * (1.0f / 512.0f) + EPS);
;                 u32x4 w;
; #pragma unroll
;                 for (int i = 0; i < 4; ++i) w[i] = pk2(v[2 * i] * rs, v[2 * i + 1] * rs);
;                 *(u32x4*)(gn + (size_t)(t0 + rr) * DIN + c) = w;
	v_lshlrev_b32_e32 v22, 16, v9
	v_and_b32_e32 v23, 0xffff0000, v9
	v_mul_f32_e32 v9, 0xbfb8aa3b, v22
	v_mul_f32_e32 v5, 0xbfb8aa3b, v23
	v_exp_f32_e32 v9, v9
	v_exp_f32_e32 v5, v5
	v_add_f32_e32 v9, 1.0, v9
	v_add_f32_e32 v5, 1.0, v5
	v_rcp_f32_e32 v24, v9
	v_rcp_f32_e32 v25, v5
	s_nop 0
	v_pk_mul_f32 v[22:23], v[24:25], v[22:23]
	v_lshlrev_b32_e32 v24, 16, v8
	v_and_b32_e32 v25, 0xffff0000, v8
	v_pk_mul_f32 v[22:23], v[22:23], v[26:27]
	v_mul_f32_e32 v5, 0xbfb8aa3b, v24
	v_lshlrev_b32_e32 v26, 16, v4
	v_and_b32_e32 v27, 0xffff0000, v4
	v_mul_f32_e32 v4, 0xbfb8aa3b, v25
	v_exp_f32_e32 v5, v5
	v_exp_f32_e32 v4, v4
	v_add_f32_e32 v5, 1.0, v5
	v_add_f32_e32 v4, 1.0, v4
	v_rcp_f32_e32 v8, v5
	v_rcp_f32_e32 v9, v4
	s_nop 0
	v_pk_mul_f32 v[4:5], v[8:9], v[24:25]
	s_nop 0
	v_pk_mul_f32 v[8:9], v[4:5], v[26:27]
	v_mov_b32_e32 v4, v22
	v_mov_b32_e32 v5, v8
	v_pk_mul_f32 v[4:5], v[4:5], v[4:5]
	v_mov_b32_e32 v24, v23
	v_mov_b32_e32 v25, v9
	v_pk_fma_f32 v[4:5], v[24:25], v[24:25], v[4:5]
	v_lshlrev_b32_e32 v24, 16, v7
	v_and_b32_e32 v25, 0xffff0000, v7
	v_mul_f32_e32 v7, 0xbfb8aa3b, v24
	v_mul_f32_e32 v3, 0xbfb8aa3b, v25
	v_exp_f32_e32 v7, v7
	v_exp_f32_e32 v3, v3
	v_add_f32_e32 v7, 1.0, v7
	v_add_f32_e32 v3, 1.0, v3
	v_rcp_f32_e32 v26, v7
	v_rcp_f32_e32 v27, v3
	s_nop 0
	v_pk_mul_f32 v[24:25], v[26:27], v[24:25]
	v_lshlrev_b32_e32 v26, 16, v6
	v_and_b32_e32 v27, 0xffff0000, v6
	v_pk_mul_f32 v[24:25], v[24:25], v[28:29]
	v_mul_f32_e32 v3, 0xbfb8aa3b, v26
	v_lshlrev_b32_e32 v28, 16, v2
	v_and_b32_e32 v29, 0xffff0000, v2
	v_mul_f32_e32 v2, 0xbfb8aa3b, v27
	v_exp_f32_e32 v3, v3
	v_exp_f32_e32 v2, v2
	v_add_f32_e32 v3, 1.0, v3
	v_add_f32_e32 v2, 1.0, v2
	v_rcp_f32_e32 v6, v3
	v_rcp_f32_e32 v7, v2
	s_nop 0
	v_pk_mul_f32 v[2:3], v[6:7], v[26:27]
	s_nop 0
	v_pk_mul_f32 v[6:7], v[2:3], v[28:29]
	v_mov_b32_e32 v3, v24
	v_mov_b32_e32 v2, v6
	v_pk_mul_f32 v[2:3], v[2:3], v[2:3]
	v_mov_b32_e32 v26, v7
	v_mov_b32_e32 v27, v25
	v_pk_fma_f32 v[2:3], v[26:27], v[26:27], v[2:3]
	v_mov_b32_e32 v27, v14
	v_mov_b32_e32 v26, v2
	v_mov_b32_e32 v14, v3
	v_pk_add_f32 v[2:3], v[26:27], v[14:15]
	v_mov_b32_e32 v14, v5
	v_mov_b32_e32 v15, v17
	v_pk_add_f32 v[2:3], v[14:15], v[2:3]
	v_mov_b32_e32 v5, v16
	v_pk_add_f32 v[2:3], v[4:5], v[2:3]
	s_nop 1
	v_add_f32_dpp v2, v2, v2 row_shr:1 row_mask:0xf bank_mask:0xf bound_ctrl:0
	v_add_f32_dpp v3, v3, v3 row_shr:1 row_mask:0xf bank_mask:0xf bound_ctrl:0
	s_nop 0
	v_add_f32_dpp v2, v2, v2 row_shr:2 row_mask:0xf bank_mask:0xf bound_ctrl:0
	v_add_f32_dpp v3, v3, v3 row_shr:2 row_mask:0xf bank_mask:0xf bound_ctrl:0
	s_nop 0
	v_add_f32_dpp v2, v2, v2 row_shr:4 row_mask:0xf bank_mask:0xf bound_ctrl:0
	v_add_f32_dpp v3, v3, v3 row_shr:4 row_mask:0xf bank_mask:0xf bound_ctrl:0
	s_nop 0
	v_add_f32_dpp v2, v2, v2 row_shr:8 row_mask:0xf bank_mask:0xf bound_ctrl:0
	v_add_f32_dpp v3, v3, v3 row_shr:8 row_mask:0xf bank_mask:0xf bound_ctrl:0
	s_nop 0
	v_add_f32_dpp v2, v2, v2 row_bcast:15 row_mask:0xa bank_mask:0xf
	v_add_f32_dpp v3, v3, v3 row_bcast:15 row_mask:0xa bank_mask:0xf
	s_nop 0
	v_add_f32_dpp v2, v2, v2 row_bcast:31 row_mask:0xc bank_mask:0xf
	v_add_f32_dpp v3, v3, v3 row_bcast:31 row_mask:0xc bank_mask:0xf
	s_nop 0
	v_readlane_b32 s24, v2, 63
	v_readlane_b32 s25, v3, 63
	s_nop 1
	v_mov_b32_e32 v2, s24
	v_mov_b32_e32 v3, s25
	s_nop 0
	v_pk_fma_f32 v[14:15], v[2:3], s[14:15], v[54:55] op_sel_hi:[1,0,0]
	s_nop 0
	v_mul_f32_e32 v2, 0x4b800000, v15
	v_cmp_gt_f32_e64 s[4:5], s91, v15
	v_cmp_gt_f32_e32 vcc, s91, v14
	s_nop 0
	v_cndmask_b32_e64 v2, v15, v2, s[4:5]
	v_rsq_f32_e32 v2, v2
	s_nop 0
	v_mul_f32_e32 v3, 0x45800000, v2
	v_cndmask_b32_e64 v16, v2, v3, s[4:5]
	v_pk_mul_f32 v[2:3], v[10:11], v[16:17] op_sel_hi:[1,0]
	v_pk_mul_f32 v[4:5], v[20:21], v[16:17] op_sel_hi:[1,0]
	v_cvt_pk_bf16_f32 v2, v2, v3
	v_cvt_pk_bf16_f32 v3, v4, v5
	v_pk_mul_f32 v[4:5], v[12:13], v[16:17] op_sel_hi:[1,0]
	v_pk_mul_f32 v[10:11], v[18:19], v[16:17] op_sel_hi:[1,0]
	v_cvt_pk_bf16_f32 v4, v4, v5
	v_cvt_pk_bf16_f32 v5, v10, v11
	global_store_dwordx4 v[56:57], v[2:5], off offset:2048
	s_nop 1
	v_mul_f32_e32 v2, 0x4b800000, v14
	v_cndmask_b32_e32 v2, v14, v2, vcc
	v_rsq_f32_e32 v2, v2
	s_nop 0
	v_mul_f32_e32 v3, 0x45800000, v2
	v_cndmask_b32_e32 v10, v2, v3, vcc
	v_pk_mul_f32 v[2:3], v[6:7], v[10:11] op_sel_hi:[1,0]
	v_pk_mul_f32 v[4:5], v[24:25], v[10:11] op_sel_hi:[1,0]
	v_cvt_pk_bf16_f32 v2, v2, v3
	v_cvt_pk_bf16_f32 v3, v4, v5
	v_pk_mul_f32 v[4:5], v[8:9], v[10:11] op_sel_hi:[1,0]
	v_pk_mul_f32 v[6:7], v[22:23], v[10:11] op_sel_hi:[1,0]
	v_cvt_pk_bf16_f32 v4, v4, v5
	v_cvt_pk_bf16_f32 v5, v6, v7
	global_store_dwordx4 v[56:57], v[2:5], off offset:3072
	s_cbranch_scc1 .LBB0_727
